# v42 + P1 work balance: the sample-row third pass of the norm phase runs on one wave of every workgroup instead of all waves of the first 32 workgroups (one XCD)
# speedup vs baseline: 1.0068x; 1.0068x over previous
.LBB0_167:
	s_or_b64 exec, exec, s[10:11]
	v_lshl_add_u64 v[0:1], v[0:1], 0, v[108:109]
	global_load_dwordx4 v[92:95], v[0:1], off nt
	global_load_dwordx4 v[84:87], v[0:1], off offset:1024 nt
	global_load_dwordx4 v[56:59], v[0:1], off offset:3072 nt
	global_load_dwordx4 v[64:67], v[0:1], off offset:2048 nt
	v_add_co_u32_e32 v2, vcc, 0x1000, v0
	v_ashrrev_i32_e32 v12, 9, v114
	s_nop 0
	v_addc_co_u32_e32 v3, vcc, 0, v1, vcc
	global_load_dwordx4 v[52:55], v[2:3], off nt
	global_load_dwordx4 v[48:51], v[2:3], off offset:1024 nt
	global_load_dwordx4 v[40:43], v[2:3], off offset:3072 nt
	global_load_dwordx4 v[44:47], v[2:3], off offset:2048 nt
	v_lshrrev_b32_e32 v2, 6, v100
	v_add_u32_e32 v13, 8, v2
	v_add_co_u32_e32 v2, vcc, 0x2000, v0
	global_load_dwordx4 v[8:11], v[102:103], off
	global_load_dwordx4 v[4:7], v[102:103], off offset:1024
	v_addc_co_u32_e32 v3, vcc, 0, v1, vcc
	global_load_dwordx4 v[36:39], v[2:3], off nt
	global_load_dwordx4 v[32:35], v[2:3], off offset:1024 nt
	global_load_dwordx4 v[28:31], v[2:3], off offset:2048 nt
	global_load_dwordx4 v[24:27], v[2:3], off offset:3072 nt
	v_cndmask_b32_e64 v12, v13, v12, s[2:3]
	v_add_co_u32_e32 v0, vcc, 0x3000, v0
	v_mad_i64_i32 v[12:13], s[2:3], v12, s16, v[110:111]
	s_nop 0
	v_addc_co_u32_e32 v1, vcc, 0, v1, vcc
	v_lshl_add_u64 v[76:77], v[12:13], 0, v[108:109]
	global_load_dwordx4 v[20:23], v[0:1], off nt
	global_load_dwordx4 v[16:19], v[0:1], off offset:1024 nt
	global_load_dwordx4 v[12:15], v[0:1], off offset:2048 nt
	s_nop 0
	global_load_dwordx4 v[0:3], v[0:1], off offset:3072 nt
	v_add_co_u32_e32 v60, vcc, s14, v76
	v_lshl_add_u64 v[112:113], v[76:77], 0, s[8:9]
	s_nop 0
	v_addc_co_u32_e32 v61, vcc, 0, v77, vcc
	global_load_dwordx4 v[96:99], v[60:61], off
	v_add_u32_e32 v114, s12, v114
	s_waitcnt vmcnt(18)
	v_pk_mul_f32 v[60:61], v[94:95], v[94:95]
	v_pk_mul_f32 v[62:63], v[92:93], v[92:93]
	s_waitcnt vmcnt(17)
	v_pk_mul_f32 v[68:69], v[86:87], v[86:87]
	v_pk_mul_f32 v[70:71], v[84:85], v[84:85]
	v_pk_mov_b32 v[78:79], v[62:63], v[60:61] op_sel:[1,0]
	v_mov_b32_e32 v63, v61
	v_pk_mov_b32 v[60:61], v[70:71], v[68:69] op_sel:[1,0]
	v_mov_b32_e32 v71, v69
	s_waitcnt vmcnt(16)
	v_mul_f32_e32 v75, v58, v58
	s_waitcnt vmcnt(15)
	v_mul_f32_e32 v72, v65, v65
	v_mul_f32_e32 v74, v67, v67
	v_pk_add_f32 v[62:63], v[78:79], v[62:63]
	v_pk_add_f32 v[60:61], v[60:61], v[70:71]
	v_mul_f32_e32 v82, v56, v56
	v_mul_f32_e32 v83, v57, v57
	v_mul_f32_e32 v80, v59, v59
	v_pk_fma_f32 v[68:69], v[64:65], v[64:65], v[72:73] op_sel_hi:[1,1,0]
	v_pk_fma_f32 v[72:73], v[66:67], v[66:67], v[74:75] op_sel_hi:[1,1,0]
	v_pk_add_f32 v[62:63], v[62:63], v[62:63] op_sel:[0,1] op_sel_hi:[1,0]
	v_pk_add_f32 v[60:61], v[60:61], v[60:61] op_sel:[0,1] op_sel_hi:[1,0]
	v_mov_b32_e32 v69, v75
	v_mov_b32_e32 v73, v80
	s_waitcnt vmcnt(14)
	v_pk_mul_f32 v[70:71], v[54:55], v[54:55]
	v_pk_mul_f32 v[74:75], v[52:53], v[52:53]
	s_waitcnt vmcnt(13)
	v_pk_mul_f32 v[78:79], v[50:51], v[50:51]
	v_pk_mul_f32 v[80:81], v[48:49], v[48:49]
	v_mov_b32_e32 v63, v82
	v_mov_b32_e32 v61, v83
	v_pk_add_f32 v[68:69], v[68:69], v[72:73]
	v_pk_mov_b32 v[72:73], v[74:75], v[70:71] op_sel:[1,0]
	v_mov_b32_e32 v75, v71
	v_pk_mov_b32 v[70:71], v[80:81], v[78:79] op_sel:[1,0]
	v_mov_b32_e32 v81, v79
	v_pk_add_f32 v[60:61], v[62:63], v[60:61]
	v_pk_add_f32 v[72:73], v[72:73], v[74:75]
	v_pk_add_f32 v[70:71], v[70:71], v[80:81]
	v_pk_add_f32 v[60:61], v[60:61], v[68:69]
	s_waitcnt vmcnt(12)
	v_mul_f32_e32 v88, v40, v40
	v_mul_f32_e32 v89, v41, v41
	v_add_f32_e32 v74, v60, v61
	v_pk_add_f32 v[60:61], v[72:73], v[72:73] op_sel:[0,1] op_sel_hi:[1,0]
	v_pk_add_f32 v[62:63], v[70:71], v[70:71] op_sel:[0,1] op_sel_hi:[1,0]
	v_mov_b32_e32 v61, v88
	v_mov_b32_e32 v63, v89
	v_pk_add_f32 v[60:61], v[60:61], v[62:63]
	s_waitcnt vmcnt(11)
	v_mul_f32_e32 v62, v45, v45
	v_mul_f32_e32 v68, v47, v47
	v_mul_f32_e32 v90, v42, v42
	v_mul_f32_e32 v75, v43, v43
	v_pk_fma_f32 v[62:63], v[44:45], v[44:45], v[62:63] op_sel_hi:[1,1,0]
	v_pk_fma_f32 v[68:69], v[46:47], v[46:47], v[68:69] op_sel_hi:[1,1,0]
	v_mov_b32_e32 v63, v90
	v_mov_b32_e32 v69, v75
	v_pk_add_f32 v[62:63], v[62:63], v[68:69]
	s_nop 0
	v_pk_add_f32 v[60:61], v[60:61], v[62:63]
	s_waitcnt vmcnt(8)
	v_pk_mul_f32 v[62:63], v[36:37], v[36:37]
	v_add_f32_e32 v78, v60, v61
	v_pk_mul_f32 v[60:61], v[38:39], v[38:39]
	s_nop 0
	v_pk_mov_b32 v[68:69], v[62:63], v[60:61] op_sel:[1,0]
	v_mov_b32_e32 v63, v61
	v_pk_add_f32 v[60:61], v[68:69], v[62:63]
	s_waitcnt vmcnt(7)
	v_pk_mul_f32 v[62:63], v[34:35], v[34:35]
	v_pk_mul_f32 v[68:69], v[32:33], v[32:33]
	v_pk_add_f32 v[60:61], v[60:61], v[60:61] op_sel:[0,1] op_sel_hi:[1,0]
	v_pk_mov_b32 v[70:71], v[68:69], v[62:63] op_sel:[1,0]
	v_mov_b32_e32 v69, v63
	v_pk_add_f32 v[62:63], v[70:71], v[68:69]
	s_waitcnt vmcnt(5)
	v_mul_f32_e32 v68, v24, v24
	v_mul_f32_e32 v69, v25, v25
	v_pk_add_f32 v[62:63], v[62:63], v[62:63] op_sel:[0,1] op_sel_hi:[1,0]
	v_mov_b32_e32 v61, v68
	v_mov_b32_e32 v63, v69
	v_pk_add_f32 v[60:61], v[60:61], v[62:63]
	v_mul_f32_e32 v62, v29, v29
	v_mul_f32_e32 v68, v31, v31
	v_mul_f32_e32 v70, v26, v26
	v_mul_f32_e32 v71, v27, v27
	v_pk_fma_f32 v[62:63], v[28:29], v[28:29], v[62:63] op_sel_hi:[1,1,0]
	v_pk_fma_f32 v[68:69], v[30:31], v[30:31], v[68:69] op_sel_hi:[1,1,0]
	v_mov_b32_e32 v63, v70
	v_mov_b32_e32 v69, v71
	v_pk_add_f32 v[62:63], v[62:63], v[68:69]
	s_nop 0
	v_pk_add_f32 v[60:61], v[60:61], v[62:63]
	s_waitcnt vmcnt(4)
	v_pk_mul_f32 v[62:63], v[20:21], v[20:21]
	v_add_f32_e32 v79, v60, v61
	v_pk_mul_f32 v[60:61], v[22:23], v[22:23]
	s_nop 0
	v_pk_mov_b32 v[68:69], v[62:63], v[60:61] op_sel:[1,0]
	v_mov_b32_e32 v63, v61
	v_pk_add_f32 v[60:61], v[68:69], v[62:63]
	s_waitcnt vmcnt(3)
	v_pk_mul_f32 v[62:63], v[18:19], v[18:19]
	v_pk_mul_f32 v[68:69], v[16:17], v[16:17]
	v_pk_add_f32 v[60:61], v[60:61], v[60:61] op_sel:[0,1] op_sel_hi:[1,0]
	v_pk_mov_b32 v[70:71], v[68:69], v[62:63] op_sel:[1,0]
	v_mov_b32_e32 v69, v63
	v_pk_add_f32 v[62:63], v[70:71], v[68:69]
	s_waitcnt vmcnt(1)
	v_mul_f32_e32 v68, v0, v0
	v_mul_f32_e32 v69, v1, v1
	v_pk_add_f32 v[62:63], v[62:63], v[62:63] op_sel:[0,1] op_sel_hi:[1,0]
	v_mov_b32_e32 v61, v68
	v_mov_b32_e32 v63, v69
	v_pk_add_f32 v[60:61], v[60:61], v[62:63]
	v_mul_f32_e32 v62, v13, v13
	v_mul_f32_e32 v70, v2, v2
	v_pk_fma_f32 v[62:63], v[12:13], v[12:13], v[62:63] op_sel_hi:[1,1,0]
	v_mul_f32_e32 v68, v15, v15
	v_mov_b32_e32 v63, v70
	ds_bpermute_b32 v70, v115, v74
	v_mul_f32_e32 v71, v3, v3
	v_pk_fma_f32 v[68:69], v[14:15], v[14:15], v[68:69] op_sel_hi:[1,1,0]
	s_nop 0
	v_mov_b32_e32 v69, v71
	v_pk_add_f32 v[62:63], v[62:63], v[68:69]
	s_waitcnt lgkmcnt(0)
	v_add_f32_e32 v69, v74, v70
	v_pk_add_f32 v[60:61], v[60:61], v[62:63]
	ds_bpermute_b32 v70, v115, v78
	v_add_f32_e32 v68, v60, v61
	ds_bpermute_b32 v71, v115, v79
	ds_bpermute_b32 v80, v115, v68
	ds_bpermute_b32 v81, v116, v69
	s_waitcnt lgkmcnt(3)
	v_add_f32_e32 v70, v78, v70
	ds_bpermute_b32 v78, v116, v70
	s_waitcnt lgkmcnt(3)
	v_add_f32_e32 v71, v79, v71
	s_waitcnt lgkmcnt(2)
	v_add_f32_e32 v68, v68, v80
	s_waitcnt lgkmcnt(1)
	v_add_f32_e32 v69, v69, v81
	ds_bpermute_b32 v79, v116, v71
	ds_bpermute_b32 v80, v116, v68
	ds_bpermute_b32 v81, v117, v69
	global_load_dwordx4 v[72:75], v[76:77], off
	global_load_dwordx4 v[60:63], v[76:77], off offset:1024
	s_waitcnt lgkmcnt(3)
	v_add_f32_e32 v78, v70, v78
	s_waitcnt lgkmcnt(2)
	v_add_f32_e32 v79, v71, v79
	s_waitcnt lgkmcnt(1)
	v_add_f32_e32 v88, v68, v80
	s_waitcnt lgkmcnt(0)
	v_add_f32_e32 v89, v69, v81
	ds_bpermute_b32 v90, v117, v78
	ds_bpermute_b32 v91, v117, v79
	ds_bpermute_b32 v100, v117, v88
	ds_bpermute_b32 v123, v118, v89
	global_load_dwordx4 v[124:127], v[112:113], off offset:1024
	global_load_dwordx4 v[128:131], v[112:113], off offset:2048
	global_load_dwordx4 v[80:83], v[102:103], off offset:2048
	global_load_dwordx4 v[68:71], v[102:103], off offset:3072
	s_waitcnt lgkmcnt(3)
	v_add_f32_e32 v132, v78, v90
	s_waitcnt lgkmcnt(2)
	v_add_f32_e32 v133, v79, v91
	s_waitcnt lgkmcnt(1)
	v_add_f32_e32 v100, v88, v100
	s_waitcnt lgkmcnt(0)
	v_add_f32_e32 v123, v89, v123
	global_load_dwordx4 v[88:91], v[76:77], off offset:2048
	s_nop 0
	global_load_dwordx4 v[76:79], v[76:77], off offset:3072
	ds_bpermute_b32 v134, v118, v132
	ds_bpermute_b32 v135, v118, v133
	ds_bpermute_b32 v137, v119, v123
	ds_bpermute_b32 v136, v118, v100
	s_waitcnt lgkmcnt(3)
	v_add_f32_e32 v138, v132, v134
	s_waitcnt lgkmcnt(2)
	v_add_f32_e32 v139, v133, v135
	global_load_dwordx4 v[132:135], v[112:113], off offset:3072
	s_waitcnt lgkmcnt(1)
	v_add_f32_e32 v123, v123, v137
	ds_bpermute_b32 v141, v120, v123
	s_waitcnt lgkmcnt(1)
	v_add_f32_e32 v100, v100, v136
	ds_bpermute_b32 v136, v119, v138
	ds_bpermute_b32 v140, v119, v100
	ds_bpermute_b32 v137, v119, v139
	s_waitcnt lgkmcnt(3)
	v_add_f32_e32 v123, v123, v141
	v_fmamk_f32 v123, v123, 0x3a800000, v121
	s_waitcnt lgkmcnt(2)
	v_add_f32_e32 v112, v138, v136
	v_mul_f32_e32 v136, 0x4f800000, v123
	v_cmp_gt_f32_e32 vcc, s17, v123
	s_waitcnt lgkmcnt(1)
	v_add_f32_e32 v100, v100, v140
	s_waitcnt lgkmcnt(0)
	v_add_f32_e32 v113, v139, v137
	v_cndmask_b32_e32 v123, v123, v136, vcc
	v_sqrt_f32_e32 v136, v123
	ds_bpermute_b32 v139, v120, v100
	ds_bpermute_b32 v137, v120, v112
	ds_bpermute_b32 v138, v120, v113
	v_add_u32_e32 v140, -1, v136
	v_fma_f32 v141, -v140, v136, v123
	v_cmp_ge_f32_e64 s[2:3], 0, v141
	v_add_u32_e32 v141, 1, v136
	s_waitcnt lgkmcnt(2)
	v_add_f32_e32 v143, v100, v139
	v_cndmask_b32_e64 v140, v136, v140, s[2:3]
	v_fma_f32 v136, -v141, v136, v123
	v_cmp_lt_f32_e64 s[2:3], 0, v136
	s_waitcnt lgkmcnt(0)
	v_add_f32_e32 v142, v113, v138
	v_cndmask_b32_e64 v136, v140, v141, s[2:3]
	v_mul_f32_e32 v140, 0x37800000, v136
	v_cndmask_b32_e32 v136, v136, v140, vcc
	v_cmp_class_f32_e32 vcc, v123, v122
	v_add_f32_e32 v141, v112, v137
	s_nop 0
	v_cndmask_b32_e32 v123, v136, v123, vcc
	v_div_scale_f32 v136, s[2:3], v123, v123, 1.0
	v_rcp_f32_e32 v140, v136
	s_nop 0
	v_fma_f32 v100, -v136, v140, 1.0
	v_fmac_f32_e32 v140, v100, v140
	v_div_scale_f32 v100, vcc, 1.0, v123, 1.0
	v_mul_f32_e32 v112, v100, v140
	v_fma_f32 v113, -v136, v112, v100
	v_fmac_f32_e32 v112, v113, v140
	v_fma_f32 v100, -v136, v112, v100
	v_div_fmas_f32 v100, v100, v140, v112
	v_div_fixup_f32 v100, v100, v123, 1.0
	v_pk_mul_f32 v[94:95], v[94:95], v[100:101] op_sel_hi:[1,0]
	v_pk_mul_f32 v[92:93], v[92:93], v[100:101] op_sel_hi:[1,0]
	v_pk_mul_f32 v[138:139], v[10:11], v[94:95]
	v_pk_mul_f32 v[136:137], v[8:9], v[92:93]
	s_waitcnt vmcnt(9)
	v_pk_add_f32 v[92:93], v[98:99], 1.0 op_sel_hi:[1,0]
	v_pk_add_f32 v[94:95], v[96:97], 1.0 op_sel_hi:[1,0]
	v_lshlrev_b64 v[112:113], 11, v[106:107]
	s_waitcnt vmcnt(8)
	v_pk_fma_f32 v[96:97], v[92:93], v[138:139], v[74:75]
	v_pk_fma_f32 v[98:99], v[94:95], v[136:137], v[72:73]
	v_lshl_add_u64 v[112:113], v[104:105], 0, v[112:113]
	v_cvt_pk_bf16_f32 v98, v98, v99
	v_cvt_pk_bf16_f32 v99, v96, v97
	v_pk_mul_f32 v[86:87], v[86:87], v[100:101] op_sel_hi:[1,0]
	v_pk_mul_f32 v[84:85], v[84:85], v[100:101] op_sel_hi:[1,0]
	global_store_dwordx2 v[112:113], v[98:99], off
	v_pk_mul_f32 v[96:97], v[4:5], v[84:85]
	v_pk_mul_f32 v[98:99], v[6:7], v[86:87]
	s_waitcnt vmcnt(7)
	v_pk_add_f32 v[84:85], v[126:127], 1.0 op_sel_hi:[1,0]
	v_pk_add_f32 v[86:87], v[124:125], 1.0 op_sel_hi:[1,0]
	v_pk_fma_f32 v[98:99], v[84:85], v[98:99], v[62:63]
	v_pk_fma_f32 v[96:97], v[86:87], v[96:97], v[60:61]
	v_pk_mul_f32 v[66:67], v[66:67], v[100:101] op_sel_hi:[1,0]
	v_cvt_pk_bf16_f32 v96, v96, v97
	v_cvt_pk_bf16_f32 v97, v98, v99
	v_pk_mul_f32 v[64:65], v[64:65], v[100:101] op_sel_hi:[1,0]
	global_store_dwordx2 v[112:113], v[96:97], off offset:512
	s_waitcnt vmcnt(6)
	v_pk_mul_f32 v[96:97], v[80:81], v[64:65]
	v_pk_mul_f32 v[98:99], v[82:83], v[66:67]
	v_pk_add_f32 v[64:65], v[130:131], 1.0 op_sel_hi:[1,0]
	v_pk_add_f32 v[66:67], v[128:129], 1.0 op_sel_hi:[1,0]
	s_waitcnt vmcnt(4)
	v_pk_fma_f32 v[98:99], v[64:65], v[98:99], v[90:91]
	v_pk_fma_f32 v[96:97], v[66:67], v[96:97], v[88:89]
	v_pk_mul_f32 v[58:59], v[58:59], v[100:101] op_sel_hi:[1,0]
	v_cvt_pk_bf16_f32 v96, v96, v97
	v_cvt_pk_bf16_f32 v97, v98, v99
	v_pk_mul_f32 v[98:99], v[70:71], v[58:59]
	v_fmamk_f32 v58, v141, 0x3a800000, v121
	v_mul_f32_e32 v59, 0x4f800000, v58
	v_cmp_gt_f32_e32 vcc, s17, v58
	v_pk_mul_f32 v[56:57], v[56:57], v[100:101] op_sel_hi:[1,0]
	global_store_dwordx2 v[112:113], v[96:97], off offset:1024
	v_cndmask_b32_e32 v100, v58, v59, vcc
	v_sqrt_f32_e32 v107, v100
	v_pk_mul_f32 v[96:97], v[68:69], v[56:57]
	s_waitcnt vmcnt(3)
	v_pk_add_f32 v[56:57], v[134:135], 1.0 op_sel_hi:[1,0]
	v_pk_add_f32 v[58:59], v[132:133], 1.0 op_sel_hi:[1,0]
	v_add_u32_e32 v123, -1, v107
	v_fma_f32 v124, -v123, v107, v100
	v_cmp_ge_f32_e64 s[2:3], 0, v124
	v_add_u32_e32 v124, 1, v107
	v_pk_fma_f32 v[98:99], v[56:57], v[98:99], v[78:79]
	v_cndmask_b32_e64 v123, v107, v123, s[2:3]
	v_fma_f32 v107, -v124, v107, v100
	v_cmp_lt_f32_e64 s[2:3], 0, v107
	v_pk_fma_f32 v[96:97], v[58:59], v[96:97], v[76:77]
	s_nop 0
	v_cndmask_b32_e64 v107, v123, v124, s[2:3]
	v_mul_f32_e32 v123, 0x37800000, v107
	v_cndmask_b32_e32 v107, v107, v123, vcc
	v_cmp_class_f32_e32 vcc, v100, v122
	v_cvt_pk_bf16_f32 v96, v96, v97
	v_cvt_pk_bf16_f32 v97, v98, v99
	v_cndmask_b32_e32 v100, v107, v100, vcc
	v_div_scale_f32 v107, s[2:3], v100, v100, 1.0
	v_rcp_f32_e32 v123, v107
	global_store_dwordx2 v[112:113], v[96:97], off offset:1536
	v_fma_f32 v96, -v107, v123, 1.0
	v_fmac_f32_e32 v123, v96, v123
	v_div_scale_f32 v96, vcc, 1.0, v100, 1.0
	v_mul_f32_e32 v97, v96, v123
	v_fma_f32 v98, -v107, v97, v96
	v_fmac_f32_e32 v97, v98, v123
	v_fma_f32 v96, -v107, v97, v96
	v_div_fmas_f32 v96, v96, v123, v97
	v_div_fixup_f32 v96, v96, v100, 1.0
	v_add_u32_e32 v98, 1, v106
	v_pk_mul_f32 v[46:47], v[46:47], v[96:97] op_sel_hi:[1,0]
	v_pk_mul_f32 v[44:45], v[44:45], v[96:97] op_sel_hi:[1,0]
	v_ashrrev_i32_e32 v99, 31, v98
	v_pk_mul_f32 v[44:45], v[80:81], v[44:45]
	v_pk_mul_f32 v[46:47], v[82:83], v[46:47]
	v_lshlrev_b64 v[98:99], 11, v[98:99]
	v_pk_fma_f32 v[46:47], v[64:65], v[46:47], v[90:91]
	v_pk_fma_f32 v[44:45], v[66:67], v[44:45], v[88:89]
	v_lshl_add_u64 v[98:99], v[104:105], 0, v[98:99]
	v_cvt_pk_bf16_f32 v44, v44, v45
	v_cvt_pk_bf16_f32 v45, v46, v47
	global_store_dwordx2 v[98:99], v[44:45], off offset:1024
	v_fmamk_f32 v44, v142, 0x3a800000, v121
	v_mul_f32_e32 v45, 0x4f800000, v44
	v_cmp_gt_f32_e32 vcc, s17, v44
	v_pk_mul_f32 v[42:43], v[42:43], v[96:97] op_sel_hi:[1,0]
	v_pk_mul_f32 v[40:41], v[40:41], v[96:97] op_sel_hi:[1,0]
	v_cndmask_b32_e32 v44, v44, v45, vcc
	v_sqrt_f32_e32 v45, v44
	v_pk_mul_f32 v[40:41], v[68:69], v[40:41]
	v_pk_mul_f32 v[42:43], v[70:71], v[42:43]
	v_pk_fma_f32 v[40:41], v[58:59], v[40:41], v[76:77]
	v_add_u32_e32 v46, -1, v45
	v_fma_f32 v47, -v46, v45, v44
	v_cmp_ge_f32_e64 s[2:3], 0, v47
	v_add_u32_e32 v47, 1, v45
	v_pk_fma_f32 v[42:43], v[56:57], v[42:43], v[78:79]
	v_cndmask_b32_e64 v46, v45, v46, s[2:3]
	v_fma_f32 v45, -v47, v45, v44
	v_cmp_lt_f32_e64 s[2:3], 0, v45
	v_cvt_pk_bf16_f32 v40, v40, v41
	v_cvt_pk_bf16_f32 v41, v42, v43
	v_cndmask_b32_e64 v45, v46, v47, s[2:3]
	v_mul_f32_e32 v46, 0x37800000, v45
	v_cndmask_b32_e32 v45, v45, v46, vcc
	v_cmp_class_f32_e32 vcc, v44, v122
	global_store_dwordx2 v[98:99], v[40:41], off offset:1536
	v_pk_mul_f32 v[54:55], v[54:55], v[96:97] op_sel_hi:[1,0]
	v_cndmask_b32_e32 v44, v45, v44, vcc
	v_div_scale_f32 v45, s[2:3], v44, v44, 1.0
	v_rcp_f32_e32 v46, v45
	v_pk_mul_f32 v[52:53], v[52:53], v[96:97] op_sel_hi:[1,0]
	v_pk_mul_f32 v[54:55], v[10:11], v[54:55]
	v_pk_mul_f32 v[52:53], v[8:9], v[52:53]
	v_fma_f32 v40, -v45, v46, 1.0
	v_fmac_f32_e32 v46, v40, v46
	v_div_scale_f32 v40, vcc, 1.0, v44, 1.0
	v_mul_f32_e32 v41, v40, v46
	v_fma_f32 v42, -v45, v41, v40
	v_fmac_f32_e32 v41, v42, v46
	v_fma_f32 v40, -v45, v41, v40
	v_div_fmas_f32 v40, v40, v46, v41
	v_div_fixup_f32 v40, v40, v44, 1.0
	v_add_u32_e32 v42, 2, v106
	v_pk_mul_f32 v[30:31], v[30:31], v[40:41] op_sel_hi:[1,0]
	v_pk_mul_f32 v[28:29], v[28:29], v[40:41] op_sel_hi:[1,0]
	v_ashrrev_i32_e32 v43, 31, v42
	v_pk_mul_f32 v[28:29], v[80:81], v[28:29]
	v_pk_mul_f32 v[30:31], v[82:83], v[30:31]
	v_lshlrev_b64 v[42:43], 11, v[42:43]
	v_pk_fma_f32 v[30:31], v[64:65], v[30:31], v[90:91]
	v_pk_fma_f32 v[28:29], v[66:67], v[28:29], v[88:89]
	v_lshl_add_u64 v[42:43], v[104:105], 0, v[42:43]
	v_cvt_pk_bf16_f32 v28, v28, v29
	v_cvt_pk_bf16_f32 v29, v30, v31
	global_store_dwordx2 v[42:43], v[28:29], off offset:1024
	v_fmamk_f32 v28, v143, 0x3a800000, v121
	v_mul_f32_e32 v29, 0x4f800000, v28
	v_cmp_gt_f32_e32 vcc, s17, v28
	v_pk_mul_f32 v[26:27], v[26:27], v[40:41] op_sel_hi:[1,0]
	v_pk_mul_f32 v[24:25], v[24:25], v[40:41] op_sel_hi:[1,0]
	v_cndmask_b32_e32 v28, v28, v29, vcc
	v_sqrt_f32_e32 v29, v28
	v_pk_mul_f32 v[24:25], v[68:69], v[24:25]
	v_pk_mul_f32 v[26:27], v[70:71], v[26:27]
	v_pk_fma_f32 v[24:25], v[58:59], v[24:25], v[76:77]
	v_add_u32_e32 v30, -1, v29
	v_fma_f32 v31, -v30, v29, v28
	v_cmp_ge_f32_e64 s[2:3], 0, v31
	v_add_u32_e32 v31, 1, v29
	v_pk_fma_f32 v[26:27], v[56:57], v[26:27], v[78:79]
	v_cndmask_b32_e64 v30, v29, v30, s[2:3]
	v_fma_f32 v29, -v31, v29, v28
	v_cmp_lt_f32_e64 s[2:3], 0, v29
	v_cvt_pk_bf16_f32 v24, v24, v25
	v_cvt_pk_bf16_f32 v25, v26, v27
	v_cndmask_b32_e64 v29, v30, v31, s[2:3]
	v_mul_f32_e32 v30, 0x37800000, v29
	v_cndmask_b32_e32 v29, v29, v30, vcc
	v_cmp_class_f32_e32 vcc, v28, v122
	global_store_dwordx2 v[42:43], v[24:25], off offset:1536
	v_pk_mul_f32 v[38:39], v[38:39], v[40:41] op_sel_hi:[1,0]
	v_cndmask_b32_e32 v28, v29, v28, vcc
	v_div_scale_f32 v29, s[2:3], v28, v28, 1.0
	v_rcp_f32_e32 v30, v29
	v_pk_mul_f32 v[36:37], v[36:37], v[40:41] op_sel_hi:[1,0]
	v_pk_mul_f32 v[38:39], v[10:11], v[38:39]
	v_pk_mul_f32 v[36:37], v[8:9], v[36:37]
	v_fma_f32 v24, -v29, v30, 1.0
	v_fmac_f32_e32 v30, v24, v30
	v_div_scale_f32 v24, vcc, 1.0, v28, 1.0
	v_mul_f32_e32 v25, v24, v30
	v_fma_f32 v26, -v29, v25, v24
	v_fmac_f32_e32 v25, v26, v30
	v_fma_f32 v24, -v29, v25, v24
	v_div_fmas_f32 v24, v24, v30, v25
	v_div_fixup_f32 v24, v24, v28, 1.0
	v_add_u32_e32 v26, 3, v106
	v_pk_mul_f32 v[22:23], v[22:23], v[24:25] op_sel_hi:[1,0]
	v_pk_mul_f32 v[20:21], v[20:21], v[24:25] op_sel_hi:[1,0]
	v_ashrrev_i32_e32 v27, 31, v26
	v_pk_mul_f32 v[8:9], v[8:9], v[20:21]
	v_pk_mul_f32 v[10:11], v[10:11], v[22:23]
	v_lshlrev_b64 v[26:27], 11, v[26:27]
	v_pk_fma_f32 v[10:11], v[92:93], v[10:11], v[74:75]
	v_pk_fma_f32 v[8:9], v[94:95], v[8:9], v[72:73]
	v_lshl_add_u64 v[26:27], v[104:105], 0, v[26:27]
	v_cvt_pk_bf16_f32 v8, v8, v9
	v_cvt_pk_bf16_f32 v9, v10, v11
	v_pk_mul_f32 v[50:51], v[50:51], v[96:97] op_sel_hi:[1,0]
	v_pk_mul_f32 v[48:49], v[48:49], v[96:97] op_sel_hi:[1,0]
	v_pk_mul_f32 v[34:35], v[34:35], v[40:41] op_sel_hi:[1,0]
	v_pk_mul_f32 v[32:33], v[32:33], v[40:41] op_sel_hi:[1,0]
	global_store_dwordx2 v[26:27], v[8:9], off
	v_pk_mul_f32 v[8:9], v[18:19], v[24:25] op_sel_hi:[1,0]
	v_pk_mul_f32 v[10:11], v[16:17], v[24:25] op_sel_hi:[1,0]
	v_pk_mul_f32 v[48:49], v[4:5], v[48:49]
	v_pk_mul_f32 v[50:51], v[6:7], v[50:51]
	v_pk_mul_f32 v[32:33], v[4:5], v[32:33]
	v_pk_mul_f32 v[34:35], v[6:7], v[34:35]
	v_pk_mul_f32 v[4:5], v[4:5], v[10:11]
	v_pk_mul_f32 v[6:7], v[6:7], v[8:9]
	v_pk_fma_f32 v[4:5], v[86:87], v[4:5], v[60:61]
	v_pk_fma_f32 v[6:7], v[84:85], v[6:7], v[62:63]
	v_cvt_pk_bf16_f32 v4, v4, v5
	v_cvt_pk_bf16_f32 v5, v6, v7
	global_store_dwordx2 v[26:27], v[4:5], off offset:512
	v_pk_mul_f32 v[4:5], v[14:15], v[24:25] op_sel_hi:[1,0]
	v_pk_mul_f32 v[6:7], v[12:13], v[24:25] op_sel_hi:[1,0]
	v_pk_mul_f32 v[2:3], v[2:3], v[24:25] op_sel_hi:[1,0]
	v_pk_mul_f32 v[0:1], v[0:1], v[24:25] op_sel_hi:[1,0]
	v_pk_mul_f32 v[6:7], v[80:81], v[6:7]
	v_pk_mul_f32 v[4:5], v[82:83], v[4:5]
	v_pk_mul_f32 v[0:1], v[68:69], v[0:1]
	v_pk_mul_f32 v[2:3], v[70:71], v[2:3]
	v_pk_fma_f32 v[54:55], v[92:93], v[54:55], v[74:75]
	v_pk_fma_f32 v[52:53], v[94:95], v[52:53], v[72:73]
	v_pk_fma_f32 v[50:51], v[84:85], v[50:51], v[62:63]
	v_pk_fma_f32 v[48:49], v[86:87], v[48:49], v[60:61]
	v_pk_fma_f32 v[38:39], v[92:93], v[38:39], v[74:75]
	v_pk_fma_f32 v[36:37], v[94:95], v[36:37], v[72:73]
	v_pk_fma_f32 v[34:35], v[84:85], v[34:35], v[62:63]
	v_pk_fma_f32 v[32:33], v[86:87], v[32:33], v[60:61]
	v_pk_fma_f32 v[4:5], v[64:65], v[4:5], v[90:91]
	v_pk_fma_f32 v[6:7], v[66:67], v[6:7], v[88:89]
	v_pk_fma_f32 v[2:3], v[56:57], v[2:3], v[78:79]
	v_pk_fma_f32 v[0:1], v[58:59], v[0:1], v[76:77]
	v_subrev_u32_e32 v247, 0x1000, v114
	v_and_b32_e32 v248, 7, v247
	v_cmp_eq_u32_e32 vcc, 0, v248
	v_lshrrev_b32_e32 v248, 3, v247
	v_add_u32_e32 v248, 0x1000, v248
	v_mov_b32_e32 v249, 0x7fff
	v_cndmask_b32_e32 v248, v249, v248, vcc
	v_cmp_gt_u32_e32 vcc, 0x800, v247
	v_cndmask_b32_e32 v114, v114, v248, vcc
	v_cmp_lt_i32_e32 vcc, s18, v114
	v_cvt_pk_bf16_f32 v52, v52, v53
	v_cvt_pk_bf16_f32 v53, v54, v55
	v_cvt_pk_bf16_f32 v48, v48, v49
	v_cvt_pk_bf16_f32 v49, v50, v51
	v_cvt_pk_bf16_f32 v36, v36, v37
	v_cvt_pk_bf16_f32 v37, v38, v39
	v_cvt_pk_bf16_f32 v32, v32, v33
	v_cvt_pk_bf16_f32 v33, v34, v35
	v_cvt_pk_bf16_f32 v6, v6, v7
	v_cvt_pk_bf16_f32 v7, v4, v5
	v_cvt_pk_bf16_f32 v0, v0, v1
	v_cvt_pk_bf16_f32 v1, v2, v3
	s_or_b64 s[6:7], vcc, s[6:7]
	v_lshlrev_b32_e32 v106, 2, v114
	global_store_dwordx2 v[98:99], v[52:53], off
	global_store_dwordx2 v[98:99], v[48:49], off offset:512
	global_store_dwordx2 v[42:43], v[36:37], off
	global_store_dwordx2 v[42:43], v[32:33], off offset:512
	global_store_dwordx2 v[26:27], v[6:7], off offset:1024
	global_store_dwordx2 v[26:27], v[0:1], off offset:1536
	s_andn2_b64 exec, exec, s[6:7]
	s_cbranch_execz .LBB0_172

	.amdhsa_kernel _Z8fwd_mega4Args
		.amdhsa_group_segment_fixed_size 0
		.amdhsa_private_segment_fixed_size 0
		.amdhsa_kernarg_size 456
		.amdhsa_user_sgpr_count 2
		.amdhsa_user_sgpr_dispatch_ptr 0
		.amdhsa_user_sgpr_queue_ptr 0
		.amdhsa_user_sgpr_kernarg_segment_ptr 1
		.amdhsa_user_sgpr_dispatch_id 0
		.amdhsa_user_sgpr_kernarg_preload_length 0
		.amdhsa_user_sgpr_kernarg_preload_offset 0
		.amdhsa_user_sgpr_private_segment_size 0
		.amdhsa_uses_dynamic_stack 0
		.amdhsa_enable_private_segment 0
		.amdhsa_system_sgpr_workgroup_id_x 1
		.amdhsa_system_sgpr_workgroup_id_y 0
		.amdhsa_system_sgpr_workgroup_id_z 0
		.amdhsa_system_sgpr_workgroup_info 0
		.amdhsa_system_vgpr_workitem_id 2
		.amdhsa_next_free_vgpr 250
		.amdhsa_next_free_sgpr 102
		.amdhsa_accum_offset 252
		.amdhsa_reserve_vcc 1
		.amdhsa_float_round_mode_32 0
		.amdhsa_float_round_mode_16_64 0
		.amdhsa_float_denorm_mode_32 3
		.amdhsa_float_denorm_mode_16_64 3
		.amdhsa_dx10_clamp 1
		.amdhsa_ieee_mode 1
		.amdhsa_fp16_overflow 0
		.amdhsa_tg_split 0
		.amdhsa_exception_fp_ieee_invalid_op 0
		.amdhsa_exception_fp_denorm_src 0
		.amdhsa_exception_fp_ieee_div_zero 0
		.amdhsa_exception_fp_ieee_overflow 0
		.amdhsa_exception_fp_ieee_underflow 0
		.amdhsa_exception_fp_ieee_inexact 0
		.amdhsa_exception_int_div_zero 0
	.end_amdhsa_kernel

amdhsa.kernels:
  - .agpr_count:     0
    .args:
      - .offset:         0
        .size:           200
        .value_kind:     by_value
      - .offset:         200
        .size:           4
        .value_kind:     hidden_block_count_x
      - .offset:         204
        .size:           4
        .value_kind:     hidden_block_count_y
      - .offset:         208
        .size:           4
        .value_kind:     hidden_block_count_z
      - .offset:         212
        .size:           2
        .value_kind:     hidden_group_size_x
      - .offset:         214
        .size:           2
        .value_kind:     hidden_group_size_y
      - .offset:         216
        .size:           2
        .value_kind:     hidden_group_size_z
      - .offset:         218
        .size:           2
        .value_kind:     hidden_remainder_x
      - .offset:         220
        .size:           2
        .value_kind:     hidden_remainder_y
      - .offset:         222
        .size:           2
        .value_kind:     hidden_remainder_z
      - .offset:         240
        .size:           8
        .value_kind:     hidden_global_offset_x
      - .offset:         248
        .size:           8
        .value_kind:     hidden_global_offset_y
      - .offset:         256
        .size:           8
        .value_kind:     hidden_global_offset_z
      - .offset:         264
        .size:           2
        .value_kind:     hidden_grid_dims
      - .offset:         288
        .size:           8
        .value_kind:     hidden_multigrid_sync_arg
      - .offset:         320
        .size:           4
        .value_kind:     hidden_dynamic_lds_size
    .group_segment_fixed_size: 0
    .kernarg_segment_align: 8
    .kernarg_segment_size: 456
    .language:       OpenCL C
    .language_version:
      - 2
      - 0
    .max_flat_workgroup_size: 512
    .name:           _Z8fwd_mega4Args
    .private_segment_fixed_size: 0
    .sgpr_count:     108
    .sgpr_spill_count: 109
    .symbol:         _Z8fwd_mega4Args.kd
    .uniform_work_group_size: 1
    .uses_dynamic_stack: false
    .vgpr_count:     250
    .vgpr_spill_count: 0
    .wavefront_size: 64
